# P7 output stage: 8 tokens normalised together - interleaved 64-lane sums, one vector evaluation of the IEEE sqrt+divide on lanes 0..7 instead of eight uniform ones; same arithmetic per token
# speedup vs baseline: 1.0940x; 1.0075x over previous
; __device__ __forceinline__ void rwkv_phase_c(const Ctx& C) {
;     ...
;             for (int u = 0; u < 8; ++u) { const int tok = tok0 + tg8 * 8 + u; vv[u] = zshift(zr, tok, 1024 + h * 64 + ci, muv); bo[u] = bon[(size_t)tok * 8 + h]; gt[u] = bf2f(Gg[(size_t)tok * GWD_ + h * 64 + ci]); }
;             f32x4 xy[2], xs[2]; ZACC(xy); ZACC(xs);
; #pragma unroll
;             for (int ks = 0; ks < 2; ++ks) {
;                 const bf16x8 a = *(const LAS bf16x8*)(Rb + mrow * BS + ks * 32 + q * 8);
;                 const bf16x8 h0 = *(const LAS bf16x8*)(SH + nc0 * BS + ks * 32 + q * 8), h1 = *(const LAS bf16x8*)(SH + (nc0 + 16) * BS + ks * 32 + q * 8);
;                 const bf16x8 l0 = *(const LAS bf16x8*)(SL + nc0 * BS + ks * 32 + q * 8), l1 = *(const LAS bf16x8*)(SL + (nc0 + 16) * BS + ks * 32 + q * 8);
;                 xy[0] = __builtin_amdgcn_mfma_f32_16x16x32_bf16(a, h0, xy[0], 0, 0, 0); xy[1] = __builtin_amdgcn_mfma_f32_16x16x32_bf16(a, h1, xy[1], 0, 0, 0);
;                 xy[0] = __builtin_amdgcn_mfma_f32_16x16x32_bf16(a, l0, xy[0], 0, 0, 0); xy[1] = __builtin_amdgcn_mfma_f32_16x16x32_bf16(a, l1, xy[1], 0, 0, 0);
;             }
;             mm_lds<false>(xs, MAT(0), Pb, mrow, nc0, q);
; #pragma unroll
;             for (int i = 0; i < 2; ++i)
; #pragma unroll
;                 for (int j = 0; j < 4; ++j) { const int r = mt * 16 + 4 * q + j, c2 = nc0 + 16 * i; MAT(1)[r * MS + c2] = xy[i][j] + yv[i][j]; }
;             __syncthreads();
; #pragma unroll
;             for (int i = 0; i < 2; ++i)
; #pragma unroll
;                 for (int j = 0; j < 4; ++j) { const int r = mt * 16 + 4 * q + j, c2 = nc0 + 16 * i; const float sv = xs[i][j] + qv[i][j];
;                     MAT(0)[r * MS + c2] = sv; const bf16_t hb = f2bf(sv); SH[r * BS + c2] = hb; SL[r * BS + c2] = f2bf(sv - bf2f(hb)); }
;             if (cc + 1 < GCH) {
;                 LAS float* Pn = MAT(2 + ((cc + 1) & 1));
;                 *(LAS f32x4*)(Pn + r0 * MS + c0) = n0; *(LAS f32x4*)(Pn + r1 * MS + c1) = n1;
;                 *(LAS u32x4*)((LAS bf16_t*)MAT(6 + ((cc + 1) & 1)) + rr8 * BS + cc8) = rn;
;             }
; #pragma unroll
;             for (int u = 0; u < 8; ++u) {
;                 const int t = tg8 * 8 + u, tok = tok0 + t;
;                 const float y = MAT(1)[t * MS + ci];
;                 const float mean = wave_sum(y) * (1.0f / 64.0f); const float dlt = y - mean;
.LBB0_1062:
	v_add_u32_e32 v244, s54, v75
	v_ashrrev_i32_e32 v245, 31, v244
	v_cmp_lt_i32_e32 vcc, 0, v42
	s_waitcnt vmcnt(31)
	v_lshlrev_b32_e32 v12, 16, v94
	s_waitcnt vmcnt(30)
	v_lshlrev_b32_e32 v2, 16, v93
	v_cndmask_b32_e64 v3, 0, 1.0, vcc
	v_fma_f32 v2, v3, v2, -v12
	v_cmp_lt_i32_e32 vcc, -1, v42
	v_fmac_f32_e32 v12, v52, v2
	s_waitcnt vmcnt(28)
	v_lshlrev_b32_e32 v13, 16, v91
	s_waitcnt vmcnt(27)
	v_lshlrev_b32_e32 v91, 16, v92
	s_waitcnt vmcnt(26)
	v_lshlrev_b32_e32 v2, 16, v90
	v_cndmask_b32_e64 v3, 0, 1.0, vcc
	v_fma_f32 v2, v3, v2, -v91
	v_fmac_f32_e32 v91, v52, v2
	s_waitcnt vmcnt(23)
	v_lshlrev_b32_e32 v90, 16, v103
	s_waitcnt vmcnt(22)
	v_lshlrev_b32_e32 v2, 16, v104
	v_fma_f32 v2, v3, v2, -v90
	v_fmac_f32_e32 v90, v52, v2
	s_waitcnt vmcnt(19)
	v_lshlrev_b32_e32 v93, 16, v98
	s_waitcnt vmcnt(18)
	v_lshlrev_b32_e32 v2, 16, v99
	v_fma_f32 v2, v3, v2, -v93
	v_fmac_f32_e32 v93, v52, v2
	s_waitcnt vmcnt(16)
	v_lshlrev_b32_e32 v94, 16, v96
	s_waitcnt vmcnt(15)
	v_lshlrev_b32_e32 v8, 16, v109
	s_waitcnt vmcnt(14)
	v_lshlrev_b32_e32 v2, 16, v110
	v_add_u32_e32 v96, 0x4400, v79
	v_fma_f32 v2, v3, v2, -v8
	v_fmac_f32_e32 v8, v52, v2
	s_waitcnt vmcnt(11)
	v_lshlrev_b32_e32 v6, 16, v107
	s_waitcnt vmcnt(10)
	v_lshlrev_b32_e32 v2, 16, v108
	v_fma_f32 v2, v3, v2, -v6
	v_fmac_f32_e32 v6, v52, v2
	s_waitcnt vmcnt(7)
	v_lshlrev_b32_e32 v4, 16, v111
	s_waitcnt vmcnt(6)
	v_lshlrev_b32_e32 v2, 16, v112
	v_fma_f32 v2, v3, v2, -v4
	v_fmac_f32_e32 v4, v52, v2
	v_lshlrev_b32_e32 v92, 16, v97
	s_waitcnt vmcnt(2)
	v_lshlrev_b32_e32 v99, 16, v102
	v_lshlrev_b32_e32 v89, 16, v89
	v_lshlrev_b32_e32 v9, 16, v106
	v_lshlrev_b32_e32 v7, 16, v105
	s_add_i32 s51, s51, 1
	s_add_i32 s10, s10, 8
	v_lshlrev_b32_e32 v5, 16, v100
	v_lshlrev_b32_e32 v2, 16, v101
	v_fma_f32 v3, v3, v99, -v2
	v_fmac_f32_e32 v2, v52, v3
	s_waitcnt vmcnt(0)
	v_lshlrev_b32_e32 v3, 16, v95
	s_waitcnt lgkmcnt(1)
	s_add_i32 s54, s54, 64
	s_cmpk_eq_i32 s54, 0x200
	v_mov_b32_e32 v216, 0xbc800000
	ds_read2_b32 v[200:201], v96 offset1:68
	ds_read2_b32 v[202:203], v96 offset0:136 offset1:204
	v_add_u32_e32 v228, 0x4800, v79
	ds_read2_b32 v[204:205], v228 offset0:16 offset1:84
	ds_read_b32 v206, v79 offset:19040
	ds_read_b32 v207, v80 offset:17408
	v_mov_b32_e32 v217, 1.0
	s_waitcnt lgkmcnt(0)
	v_add_f32_dpp v208, v200, v200 quad_perm:[1,0,3,2] row_mask:0xf bank_mask:0xf
	v_add_f32_dpp v209, v201, v201 quad_perm:[1,0,3,2] row_mask:0xf bank_mask:0xf
	v_add_f32_dpp v210, v202, v202 quad_perm:[1,0,3,2] row_mask:0xf bank_mask:0xf
	v_add_f32_dpp v211, v203, v203 quad_perm:[1,0,3,2] row_mask:0xf bank_mask:0xf
	v_add_f32_dpp v212, v204, v204 quad_perm:[1,0,3,2] row_mask:0xf bank_mask:0xf
	v_add_f32_dpp v213, v205, v205 quad_perm:[1,0,3,2] row_mask:0xf bank_mask:0xf
	v_add_f32_dpp v214, v206, v206 quad_perm:[1,0,3,2] row_mask:0xf bank_mask:0xf
	v_add_f32_dpp v215, v207, v207 quad_perm:[1,0,3,2] row_mask:0xf bank_mask:0xf
	v_add_f32_dpp v208, v208, v208 quad_perm:[2,3,0,1] row_mask:0xf bank_mask:0xf
	v_add_f32_dpp v209, v209, v209 quad_perm:[2,3,0,1] row_mask:0xf bank_mask:0xf
	v_add_f32_dpp v210, v210, v210 quad_perm:[2,3,0,1] row_mask:0xf bank_mask:0xf
	v_add_f32_dpp v211, v211, v211 quad_perm:[2,3,0,1] row_mask:0xf bank_mask:0xf
	v_add_f32_dpp v212, v212, v212 quad_perm:[2,3,0,1] row_mask:0xf bank_mask:0xf
	v_add_f32_dpp v213, v213, v213 quad_perm:[2,3,0,1] row_mask:0xf bank_mask:0xf
	v_add_f32_dpp v214, v214, v214 quad_perm:[2,3,0,1] row_mask:0xf bank_mask:0xf
	v_add_f32_dpp v215, v215, v215 quad_perm:[2,3,0,1] row_mask:0xf bank_mask:0xf
	v_add_f32_dpp v208, v208, v208 row_half_mirror row_mask:0xf bank_mask:0xf
	v_add_f32_dpp v209, v209, v209 row_half_mirror row_mask:0xf bank_mask:0xf
	v_add_f32_dpp v210, v210, v210 row_half_mirror row_mask:0xf bank_mask:0xf
	v_add_f32_dpp v211, v211, v211 row_half_mirror row_mask:0xf bank_mask:0xf
	v_add_f32_dpp v212, v212, v212 row_half_mirror row_mask:0xf bank_mask:0xf
	v_add_f32_dpp v213, v213, v213 row_half_mirror row_mask:0xf bank_mask:0xf
	v_add_f32_dpp v214, v214, v214 row_half_mirror row_mask:0xf bank_mask:0xf
	v_add_f32_dpp v215, v215, v215 row_half_mirror row_mask:0xf bank_mask:0xf
	v_add_f32_dpp v208, v208, v208 row_mirror row_mask:0xf bank_mask:0xf
	v_add_f32_dpp v209, v209, v209 row_mirror row_mask:0xf bank_mask:0xf
	v_add_f32_dpp v210, v210, v210 row_mirror row_mask:0xf bank_mask:0xf
	v_add_f32_dpp v211, v211, v211 row_mirror row_mask:0xf bank_mask:0xf
	v_add_f32_dpp v212, v212, v212 row_mirror row_mask:0xf bank_mask:0xf
	v_add_f32_dpp v213, v213, v213 row_mirror row_mask:0xf bank_mask:0xf
	v_add_f32_dpp v214, v214, v214 row_mirror row_mask:0xf bank_mask:0xf
	v_add_f32_dpp v215, v215, v215 row_mirror row_mask:0xf bank_mask:0xf
	v_add_f32_dpp v208, v208, v208 row_bcast:15 row_mask:0xa bank_mask:0xf
	v_add_f32_dpp v209, v209, v209 row_bcast:15 row_mask:0xa bank_mask:0xf
	v_add_f32_dpp v210, v210, v210 row_bcast:15 row_mask:0xa bank_mask:0xf
	v_add_f32_dpp v211, v211, v211 row_bcast:15 row_mask:0xa bank_mask:0xf
	v_add_f32_dpp v212, v212, v212 row_bcast:15 row_mask:0xa bank_mask:0xf
	v_add_f32_dpp v213, v213, v213 row_bcast:15 row_mask:0xa bank_mask:0xf
	v_add_f32_dpp v214, v214, v214 row_bcast:15 row_mask:0xa bank_mask:0xf
	v_add_f32_dpp v215, v215, v215 row_bcast:15 row_mask:0xa bank_mask:0xf
	v_add_f32_dpp v208, v208, v208 row_bcast:31 row_mask:0xc bank_mask:0xf
	v_add_f32_dpp v209, v209, v209 row_bcast:31 row_mask:0xc bank_mask:0xf
	v_add_f32_dpp v210, v210, v210 row_bcast:31 row_mask:0xc bank_mask:0xf
	v_add_f32_dpp v211, v211, v211 row_bcast:31 row_mask:0xc bank_mask:0xf
	v_add_f32_dpp v212, v212, v212 row_bcast:31 row_mask:0xc bank_mask:0xf
; __device__ __forceinline__ float wave_sum(float v) {
;     v += dpp_f(v, 0); v += dpp_f(v, 1); v += dpp_f(v, 2); v += dpp_f(v, 3);
;     const int vi = __float_as_int(v);
;     const float s0 = __int_as_float(__builtin_amdgcn_readlane(vi, 0)), s1 = __int_as_float(__builtin_amdgcn_readlane(vi, 16)), s2 = __int_as_float(__builtin_amdgcn_readlane(vi, 32)), s3 = __int_as_float(__builtin_amdgcn_readlane(vi, 48));
;     return (s0 + s1) + (s2 + s3);
; __device__ __forceinline__ void rwkv_phase_c(const Ctx& C) {
;     ...
;             for (int u = 0; u < 8; ++u) {
;                 const int t = tg8 * 8 + u, tok = tok0 + t;
;                 const float y = MAT(1)[t * MS + ci];
;                 const float mean = wave_sum(y) * (1.0f / 64.0f); const float dlt = y - mean;
;                 const float var = wave_sum(dlt * dlt) * (1.0f / 64.0f);
;                 const float yn = dlt * (1.0f / sqrtf(var + 64e-5f)) * gg + gb;
	v_add_f32_dpp v213, v213, v213 row_bcast:31 row_mask:0xc bank_mask:0xf
	v_add_f32_dpp v214, v214, v214 row_bcast:31 row_mask:0xc bank_mask:0xf
	v_add_f32_dpp v215, v215, v215 row_bcast:31 row_mask:0xc bank_mask:0xf
	v_readlane_b32 s68, v208, 63
	v_readlane_b32 s69, v209, 63
	v_readlane_b32 s70, v210, 63
	v_readlane_b32 s71, v211, 63
	v_readlane_b32 s98, v212, 63
	v_readlane_b32 s99, v213, 63
	v_readlane_b32 s100, v214, 63
	v_readlane_b32 s101, v215, 63
	v_fmac_f32_e32 v200, s68, v216
	v_fmac_f32_e32 v201, s69, v216
	v_fmac_f32_e32 v202, s70, v216
	v_fmac_f32_e32 v203, s71, v216
	v_fmac_f32_e32 v204, s98, v216
	v_fmac_f32_e32 v205, s99, v216
	v_fmac_f32_e32 v206, s100, v216
	v_fmac_f32_e32 v207, s101, v216
	v_mul_f32_e32 v208, v200, v200
	v_mul_f32_e32 v209, v201, v201
	v_mul_f32_e32 v210, v202, v202
	v_mul_f32_e32 v211, v203, v203
	v_mul_f32_e32 v212, v204, v204
	v_mul_f32_e32 v213, v205, v205
	v_mul_f32_e32 v214, v206, v206
	v_mul_f32_e32 v215, v207, v207
	v_mov_b32_dpp v208, v208 quad_perm:[1,0,3,2] row_mask:0xf bank_mask:0xf
	v_mov_b32_dpp v209, v209 quad_perm:[1,0,3,2] row_mask:0xf bank_mask:0xf
	v_mov_b32_dpp v210, v210 quad_perm:[1,0,3,2] row_mask:0xf bank_mask:0xf
	v_mov_b32_dpp v211, v211 quad_perm:[1,0,3,2] row_mask:0xf bank_mask:0xf
	v_mov_b32_dpp v212, v212 quad_perm:[1,0,3,2] row_mask:0xf bank_mask:0xf
	v_mov_b32_dpp v213, v213 quad_perm:[1,0,3,2] row_mask:0xf bank_mask:0xf
	v_mov_b32_dpp v214, v214 quad_perm:[1,0,3,2] row_mask:0xf bank_mask:0xf
	v_mov_b32_dpp v215, v215 quad_perm:[1,0,3,2] row_mask:0xf bank_mask:0xf
	v_fmac_f32_e32 v208, v200, v200
	v_fmac_f32_e32 v209, v201, v201
	v_fmac_f32_e32 v210, v202, v202
	v_fmac_f32_e32 v211, v203, v203
	v_fmac_f32_e32 v212, v204, v204
	v_fmac_f32_e32 v213, v205, v205
	v_fmac_f32_e32 v214, v206, v206
	v_fmac_f32_e32 v215, v207, v207
	v_add_f32_dpp v208, v208, v208 quad_perm:[2,3,0,1] row_mask:0xf bank_mask:0xf
	v_add_f32_dpp v209, v209, v209 quad_perm:[2,3,0,1] row_mask:0xf bank_mask:0xf
	v_add_f32_dpp v210, v210, v210 quad_perm:[2,3,0,1] row_mask:0xf bank_mask:0xf
	v_add_f32_dpp v211, v211, v211 quad_perm:[2,3,0,1] row_mask:0xf bank_mask:0xf
	v_add_f32_dpp v212, v212, v212 quad_perm:[2,3,0,1] row_mask:0xf bank_mask:0xf
	v_add_f32_dpp v213, v213, v213 quad_perm:[2,3,0,1] row_mask:0xf bank_mask:0xf
	v_add_f32_dpp v214, v214, v214 quad_perm:[2,3,0,1] row_mask:0xf bank_mask:0xf
	v_add_f32_dpp v215, v215, v215 quad_perm:[2,3,0,1] row_mask:0xf bank_mask:0xf
	v_add_f32_dpp v208, v208, v208 row_half_mirror row_mask:0xf bank_mask:0xf
	v_add_f32_dpp v209, v209, v209 row_half_mirror row_mask:0xf bank_mask:0xf
	v_add_f32_dpp v210, v210, v210 row_half_mirror row_mask:0xf bank_mask:0xf
	v_add_f32_dpp v211, v211, v211 row_half_mirror row_mask:0xf bank_mask:0xf
	v_add_f32_dpp v212, v212, v212 row_half_mirror row_mask:0xf bank_mask:0xf
	v_add_f32_dpp v213, v213, v213 row_half_mirror row_mask:0xf bank_mask:0xf
	v_add_f32_dpp v214, v214, v214 row_half_mirror row_mask:0xf bank_mask:0xf
	v_add_f32_dpp v215, v215, v215 row_half_mirror row_mask:0xf bank_mask:0xf
	v_add_f32_dpp v208, v208, v208 row_mirror row_mask:0xf bank_mask:0xf
	v_add_f32_dpp v209, v209, v209 row_mirror row_mask:0xf bank_mask:0xf
	v_add_f32_dpp v210, v210, v210 row_mirror row_mask:0xf bank_mask:0xf
	v_add_f32_dpp v211, v211, v211 row_mirror row_mask:0xf bank_mask:0xf
	v_add_f32_dpp v212, v212, v212 row_mirror row_mask:0xf bank_mask:0xf
	v_add_f32_dpp v213, v213, v213 row_mirror row_mask:0xf bank_mask:0xf
	v_add_f32_dpp v214, v214, v214 row_mirror row_mask:0xf bank_mask:0xf
	v_add_f32_dpp v215, v215, v215 row_mirror row_mask:0xf bank_mask:0xf
	v_add_f32_dpp v208, v208, v208 row_bcast:15 row_mask:0xa bank_mask:0xf
	v_add_f32_dpp v209, v209, v209 row_bcast:15 row_mask:0xa bank_mask:0xf
	v_add_f32_dpp v210, v210, v210 row_bcast:15 row_mask:0xa bank_mask:0xf
	v_add_f32_dpp v211, v211, v211 row_bcast:15 row_mask:0xa bank_mask:0xf
	v_add_f32_dpp v212, v212, v212 row_bcast:15 row_mask:0xa bank_mask:0xf
	v_add_f32_dpp v213, v213, v213 row_bcast:15 row_mask:0xa bank_mask:0xf
	v_add_f32_dpp v214, v214, v214 row_bcast:15 row_mask:0xa bank_mask:0xf
	v_add_f32_dpp v215, v215, v215 row_bcast:15 row_mask:0xa bank_mask:0xf
	v_add_f32_dpp v208, v208, v208 row_bcast:31 row_mask:0xc bank_mask:0xf
	v_add_f32_dpp v209, v209, v209 row_bcast:31 row_mask:0xc bank_mask:0xf
	v_add_f32_dpp v210, v210, v210 row_bcast:31 row_mask:0xc bank_mask:0xf
	v_add_f32_dpp v211, v211, v211 row_bcast:31 row_mask:0xc bank_mask:0xf
; __device__ __forceinline__ bf16_t f2bf(float f) { return (bf16_t)(pk2(f, 0.f) & 0xffffu); }
; __device__ __forceinline__ void rwkv_phase_c(const Ctx& C) {
;     ...
;                 const float mean = wave_sum(y) * (1.0f / 64.0f); const float dlt = y - mean;
;                 const float var = wave_sum(dlt * dlt) * (1.0f / 64.0f);
;                 const float yn = dlt * (1.0f / sqrtf(var + 64e-5f)) * gg + gb;
;                 ycat[(size_t)tok * D_ + h * 64 + ci] = f2bf((yn + bo[u] * vv[u]) * gt[u]);
;             }
;             __syncthreads();
	v_add_f32_dpp v212, v212, v212 row_bcast:31 row_mask:0xc bank_mask:0xf
	v_add_f32_dpp v213, v213, v213 row_bcast:31 row_mask:0xc bank_mask:0xf
	v_add_f32_dpp v214, v214, v214 row_bcast:31 row_mask:0xc bank_mask:0xf
	v_add_f32_dpp v215, v215, v215 row_bcast:31 row_mask:0xc bank_mask:0xf
	v_readlane_b32 s68, v208, 63
	v_readlane_b32 s69, v209, 63
	v_readlane_b32 s70, v210, 63
	v_readlane_b32 s71, v211, 63
	v_readlane_b32 s98, v212, 63
	v_readlane_b32 s99, v213, 63
	v_readlane_b32 s100, v214, 63
	v_readlane_b32 s101, v215, 63
	v_writelane_b32 v217, s68, 0
	v_writelane_b32 v217, s69, 1
	v_writelane_b32 v217, s70, 2
	v_writelane_b32 v217, s71, 3
	v_writelane_b32 v217, s98, 4
	v_writelane_b32 v217, s99, 5
	v_writelane_b32 v217, s100, 6
	v_writelane_b32 v217, s101, 7
	v_fmamk_f32 v218, v217, 0x3c800000, v1
	v_mul_f32_e32 v219, 0x4f800000, v218
	v_cmp_gt_f32_e32 vcc, s48, v218
	s_nop 1
	v_cndmask_b32_e32 v220, v218, v219, vcc
	v_sqrt_f32_e32 v221, v220
	s_nop 0
	v_add_u32_e32 v222, -1, v221
	v_fma_f32 v223, -v222, v221, v220
	v_cmp_ge_f32_e64 s[6:7], 0, v223
	v_add_u32_e32 v223, 1, v221
	s_nop 0
	v_cndmask_b32_e64 v222, v221, v222, s[6:7]
	v_fma_f32 v221, -v223, v221, v220
	v_cmp_lt_f32_e64 s[6:7], 0, v221
	s_nop 1
	v_cndmask_b32_e64 v221, v222, v223, s[6:7]
	v_mul_f32_e32 v222, 0x37800000, v221
	v_cndmask_b32_e32 v221, v221, v222, vcc
	v_cmp_class_f32_e32 vcc, v220, v44
	s_nop 1
	v_cndmask_b32_e32 v220, v221, v220, vcc
	v_div_scale_f32 v221, s[6:7], v220, v220, 1.0
	v_rcp_f32_e32 v222, v221
	s_nop 0
	v_fma_f32 v224, -v221, v222, 1.0
	v_fmac_f32_e32 v222, v224, v222
	v_div_scale_f32 v224, vcc, 1.0, v220, 1.0
	v_mul_f32_e32 v225, v224, v222
	v_fma_f32 v223, -v221, v225, v224
	v_fmac_f32_e32 v225, v223, v222
	v_fma_f32 v224, -v221, v225, v224
	v_div_fmas_f32 v224, v224, v222, v225
	v_div_fixup_f32 v227, v224, v220, 1.0
	s_nop 0
	v_readlane_b32 s68, v227, 0
	v_readlane_b32 s69, v227, 1
	v_readlane_b32 s70, v227, 2
	v_readlane_b32 s71, v227, 3
	v_readlane_b32 s98, v227, 4
	v_readlane_b32 s99, v227, 5
	v_readlane_b32 s100, v227, 6
	v_readlane_b32 s101, v227, 7
	v_mul_f32_e32 v208, s68, v200
	v_mul_f32_e32 v209, s69, v201
	v_mul_f32_e32 v210, s70, v202
	v_mul_f32_e32 v211, s71, v203
	v_mul_f32_e32 v212, s98, v204
	v_mul_f32_e32 v213, s99, v205
	v_mul_f32_e32 v214, s100, v206
	v_mul_f32_e32 v215, s101, v207
	v_fma_f32 v208, v50, v208, v51
	v_fma_f32 v209, v50, v209, v51
	v_fma_f32 v210, v50, v210, v51
	v_fma_f32 v211, v50, v211, v51
	v_fma_f32 v212, v50, v212, v51
	v_fma_f32 v213, v50, v213, v51
	v_fma_f32 v214, v50, v214, v51
	v_fma_f32 v215, v50, v215, v51
	v_fmac_f32_e32 v208, v88, v12
	v_fmac_f32_e32 v209, v87, v91
	v_fmac_f32_e32 v210, v86, v90
	v_fmac_f32_e32 v211, v85, v93
	v_fmac_f32_e32 v212, v84, v8
	v_fmac_f32_e32 v213, v82, v6
	v_fmac_f32_e32 v214, v83, v4
	v_fmac_f32_e32 v215, v81, v2
	v_mul_f32_e32 v208, v208, v13
	v_mul_f32_e32 v209, v209, v89
	v_mul_f32_e32 v210, v210, v92
	v_mul_f32_e32 v211, v211, v94
	v_mul_f32_e32 v212, v212, v9
	v_mul_f32_e32 v213, v213, v7
	v_mul_f32_e32 v214, v214, v5
	v_mul_f32_e32 v215, v215, v3
	v_cvt_pk_bf16_f32 v208, v208, s0
	v_cvt_pk_bf16_f32 v209, v209, s0
	v_cvt_pk_bf16_f32 v210, v210, s0
	v_cvt_pk_bf16_f32 v211, v211, s0
	v_cvt_pk_bf16_f32 v212, v212, s0
	v_cvt_pk_bf16_f32 v213, v213, s0
	v_cvt_pk_bf16_f32 v214, v214, s0
	v_cvt_pk_bf16_f32 v215, v215, s0
	v_lshlrev_b64 v[228:229], 11, v[42:43]
	v_lshlrev_b64 v[230:231], 11, v[40:41]
	v_lshlrev_b64 v[232:233], 11, v[38:39]
	v_lshlrev_b64 v[234:235], 11, v[36:37]
	v_lshlrev_b64 v[236:237], 11, v[34:35]
	v_lshlrev_b64 v[238:239], 11, v[32:33]
	v_lshlrev_b64 v[240:241], 11, v[30:31]
	v_lshlrev_b64 v[242:243], 11, v[244:245]
	v_lshl_add_u64 v[228:229], v[22:23], 0, v[228:229]
	v_lshl_add_u64 v[230:231], v[22:23], 0, v[230:231]
	v_lshl_add_u64 v[232:233], v[22:23], 0, v[232:233]
	v_lshl_add_u64 v[234:235], v[22:23], 0, v[234:235]
	v_lshl_add_u64 v[236:237], v[22:23], 0, v[236:237]
	v_lshl_add_u64 v[238:239], v[22:23], 0, v[238:239]
	v_lshl_add_u64 v[240:241], v[22:23], 0, v[240:241]
	v_lshl_add_u64 v[242:243], v[22:23], 0, v[242:243]
	global_store_short v[228:229], v208, off
	global_store_short v[230:231], v209, off
	global_store_short v[232:233], v210, off
	global_store_short v[234:235], v211, off
	global_store_short v[236:237], v212, off
	global_store_short v[238:239], v213, off
	global_store_short v[240:241], v214, off
	global_store_short v[242:243], v215, off
	s_barrier
	s_cbranch_scc1 .LBB0_1060
